# memory-attention K/V staging: all sixteen row loads of the (sequence, head) image issued before the first LDS write
# baseline (speedup 1.0000x reference)
; #define LAS __attribute__((address_space(3)))
; template <int DH, int NT, int MODE>
; __device__ __forceinline__ void attn_item(const AttnP& P, LAS unsigned char* vl, int lane_in, const LAS unsigned char* kl = nullptr) {
;     ...
;     bf16x8 qf[NT][KS];
; #pragma unroll
;     for (int i = 0; i < NT; ++i)
; #pragma unroll
;         for (int ks = 0; ks < KS; ++ks) qf[i][ks] = *(const bf16x8*)(P.q + (size_t)i * P.q_toff + (size_t)fr * P.q_rs + ks * 32 + g * 8);
;     f32x4 o[NT][ND]; float mrun[NT], lrun[NT];
; #pragma unroll
;     for (int i = 0; i < NT; ++i) {
; #pragma unroll
;         for (int d = 0; d < ND; ++d) o[i][d] = (f32x4){0.f, 0.f, 0.f, 0.f};
;         mrun[i] = SINK ? P.sink2[i] : -1e30f; lrun[i] = (SINK && g == 0) ? 1.f : 0.f; }
;     bf16x8 kf[2][KS]; u32x4 vr[NVL];
;     constexpr int CPR = DH / 8;
;     const int kmax = P.sub_len - 1, klo = P.k_lo, kvrs = P.kv_rs;
;     const bf16_t* kbase = P.k + g * 8; const bf16_t* vbase = P.v;
;     if (!INLDS) {
; #pragma unroll
;         for (int a = 0; a < 2; ++a) { int kp = klo + 16 * a + fr; kp = kp < 0 ? 0 : (kp > kmax ? kmax : kp);
; #pragma unroll
;             for (int ks = 0; ks < KS; ++ks) kf[a][ks] = *(const bf16x8*)(kbase + (size_t)kp * kvrs + ks * 32); }
; #pragma unroll
;         for (int it = 0; it < NVL; ++it) { const int idx = it * 64 + lane, r = idx / CPR, ch = idx % CPR; int kp = klo + r; kp = kp < 0 ? 0 : (kp > kmax ? kmax : kp);
;             vr[it] = *(const u32x4*)(vbase + (size_t)kp * kvrs + ch * 8); }
;     }
;     const LAS unsigned char* vrd = vl + (4 * g + (fr >> 2)) * VP + 8 * (fr & 3);
;     const float qbase = (float)(4 * g - P.qpos0 - fr);
; __global__ void __launch_bounds__(512, 2) mega_fwd(Args args) {
;     ...
;                         const bf16_t* mb = memkv + (size_t)(memrow0 + sq * NMEM) * 2048 + l * 1024 + hh * 128;
;                         __syncthreads();
; #pragma unroll 2
;                         for (int j = 0; j < 8; ++j) { const int idx = j * 512 + (int)threadIdx.x, rrow = idx >> 4, pc = idx & 15;
;                             const u32x4 kv = *(const u32x4*)(mb + (size_t)rrow * 2048 + pc * 8), vv = *(const u32x4*)(mb + 512 + (size_t)rrow * 2048 + pc * 8);
;                             *(LAS u32x4*)(lds + rrow * 288 + pc * 16) = kv; *(LAS u32x4*)(lds + 73728 + rrow * 288 + pc * 16) = vv; }
;                         __syncthreads();
.LBB0_45:
	v_lshl_add_u64 v[4:5], v[2:3], 0, s[38:39]
	v_lshl_add_u64 v[6:7], v[0:1], 0, s[38:39]
	v_add_co_u32_e32 v4, vcc, 0x7600000, v4
	s_nop 1
	v_addc_co_u32_e32 v5, vcc, 0, v5, vcc
	v_add_co_u32_e32 v6, vcc, 0x7600000, v6
	s_nop 1
	v_addc_co_u32_e32 v7, vcc, 0, v7, vcc
	v_add_u32_e32 v72, 0x12000, v198
	v_add_u32_e32 v73, 0x12000, v197
	global_load_dwordx4 v[8:11], v[4:5], off
	global_load_dwordx4 v[12:15], v[4:5], off offset:1024
	global_load_dwordx4 v[16:19], v[6:7], off
	global_load_dwordx4 v[20:23], v[6:7], off offset:1024
	v_lshl_add_u64 v[4:5], v[4:5], 0, s[56:57]
	v_lshl_add_u64 v[6:7], v[6:7], 0, s[56:57]
	global_load_dwordx4 v[24:27], v[4:5], off
	global_load_dwordx4 v[28:31], v[4:5], off offset:1024
	global_load_dwordx4 v[32:35], v[6:7], off
	global_load_dwordx4 v[36:39], v[6:7], off offset:1024
	v_lshl_add_u64 v[4:5], v[4:5], 0, s[56:57]
	v_lshl_add_u64 v[6:7], v[6:7], 0, s[56:57]
	global_load_dwordx4 v[40:43], v[4:5], off
	global_load_dwordx4 v[44:47], v[4:5], off offset:1024
	global_load_dwordx4 v[48:51], v[6:7], off
	global_load_dwordx4 v[52:55], v[6:7], off offset:1024
	v_lshl_add_u64 v[4:5], v[4:5], 0, s[56:57]
	v_lshl_add_u64 v[6:7], v[6:7], 0, s[56:57]
	global_load_dwordx4 v[56:59], v[4:5], off
	global_load_dwordx4 v[60:63], v[4:5], off offset:1024
	global_load_dwordx4 v[64:67], v[6:7], off
	global_load_dwordx4 v[68:71], v[6:7], off offset:1024
	s_waitcnt vmcnt(15)
	ds_write_b128 v198, v[8:11]
	s_waitcnt vmcnt(14)
	ds_write_b128 v72, v[12:15]
	s_waitcnt vmcnt(13)
	ds_write_b128 v197, v[16:19]
	s_waitcnt vmcnt(12)
	ds_write_b128 v73, v[20:23]
	s_waitcnt vmcnt(11)
	ds_write_b128 v198, v[24:27] offset:18432
	s_waitcnt vmcnt(10)
	ds_write_b128 v72, v[28:31] offset:18432
	s_waitcnt vmcnt(9)
	ds_write_b128 v197, v[32:35] offset:18432
	s_waitcnt vmcnt(8)
	ds_write_b128 v73, v[36:39] offset:18432
	s_waitcnt vmcnt(7)
	ds_write_b128 v198, v[40:43] offset:36864
	s_waitcnt vmcnt(6)
	ds_write_b128 v72, v[44:47] offset:36864
	s_waitcnt vmcnt(5)
	ds_write_b128 v197, v[48:51] offset:36864
	s_waitcnt vmcnt(4)
	ds_write_b128 v73, v[52:55] offset:36864
	s_waitcnt vmcnt(3)
	ds_write_b128 v198, v[56:59] offset:55296
	s_waitcnt vmcnt(2)
	ds_write_b128 v72, v[60:63] offset:55296
	s_waitcnt vmcnt(1)
	ds_write_b128 v197, v[64:67] offset:55296
	s_waitcnt vmcnt(0)
	ds_write_b128 v73, v[68:71] offset:55296
	s_mov_b32 s35, 0x12000
	s_mul_i32 s30, s30, s25
	s_sub_i32 s4, s42, s30
	s_lshl_b32 s4, s4, 8
	s_lshl_b32 s5, s31, s22
	s_add_i32 s4, s4, s27
	s_add_i32 s44, s4, s5
	s_and_b32 s43, s34, 0x180
	s_mul_i32 s5, s44, 0x1600
	s_mul_hi_i32 s4, s44, 0x1600
	s_add_u32 s5, s92, s5
	s_addc_u32 s6, s93, s4
	s_lshl_b32 s4, s43, 1
	s_add_u32 s4, s5, s4
	v_mov_b32_e32 v6, v170
	s_waitcnt lgkmcnt(0)
	s_barrier
	s_addc_u32 s5, s6, 0
	v_mov_b64_e32 v[0:1], s[4:5]
	v_ashrrev_i32_e32 v109, 4, v6
	v_and_b32_e32 v108, 15, v6
	v_lshlrev_b32_e32 v2, 3, v109
	v_mad_u64_u32 v[0:1], s[4:5], v108, s14, v[0:1]
	v_ashrrev_i32_e32 v3, 31, v2
	v_lshl_add_u64 v[0:1], v[2:3], 1, v[0:1]
	s_mov_b64 s[4:5], 0x1200
	v_lshl_add_u64 v[2:3], v[0:1], 0, s[4:5]
	s_movk_i32 s4, 0x1000
	v_add_co_u32_e32 v4, vcc, s4, v0
	s_mov_b32 s4, 0x17000
	s_nop 0
	v_addc_co_u32_e32 v5, vcc, 0, v1, vcc
	v_add_co_u32_e32 v0, vcc, s4, v0
	global_load_dwordx4 v[64:67], v[2:3], off offset:64
	global_load_dwordx4 v[68:71], v[2:3], off offset:128
	global_load_dwordx4 v[72:75], v[4:5], off offset:512
	global_load_dwordx4 v[76:79], v[2:3], off offset:192
	v_addc_co_u32_e32 v1, vcc, 0, v1, vcc
	global_load_dwordx4 v[80:83], v[0:1], off offset:512
	global_load_dwordx4 v[84:87], v[0:1], off offset:576
	global_load_dwordx4 v[88:91], v[0:1], off offset:640
	global_load_dwordx4 v[92:95], v[0:1], off offset:704
	s_movk_i32 s4, 0x480
	v_bfe_u32 v1, v6, 2, 2
	v_mul_lo_u32 v3, v109, s4
	s_movk_i32 s4, 0x120
	v_lshlrev_b32_e32 v2, 3, v6
	v_mad_u32_u24 v1, v1, s4, v3
	v_and_or_b32 v1, v2, 24, v1
	v_and_b32_e32 v0, -16, v6
	v_add_u32_e32 v110, 0, v1
	v_mul_u32_u24_e32 v1, 0x120, v108
	v_mov_b32_e32 v56, 0
	s_mov_b32 s45, 0
	v_add3_u32 v111, v1, v0, 0
	v_mov_b32_e32 v100, 0xf149f2ca
	v_mov_b32_e32 v96, 0xf149f2ca
	v_mov_b32_e32 v57, v56
	v_mov_b32_e32 v58, v56
	v_mov_b32_e32 v59, v56
	v_mov_b32_e32 v60, v56
	v_mov_b32_e32 v61, v56
	v_mov_b32_e32 v62, v56
	v_mov_b32_e32 v63, v56
	v_mov_b32_e32 v52, v56
	v_mov_b32_e32 v53, v56
	v_mov_b32_e32 v54, v56
	v_mov_b32_e32 v55, v56
	v_mov_b32_e32 v48, v56
	v_mov_b32_e32 v49, v56
	v_mov_b32_e32 v50, v56
	v_mov_b32_e32 v51, v56
	v_mov_b32_e32 v44, v56
	v_mov_b32_e32 v45, v56
	v_mov_b32_e32 v46, v56
	v_mov_b32_e32 v47, v56
	v_mov_b32_e32 v40, v56
	v_mov_b32_e32 v41, v56
	v_mov_b32_e32 v42, v56
	v_mov_b32_e32 v43, v56
	v_mov_b32_e32 v36, v56
	v_mov_b32_e32 v37, v56
	v_mov_b32_e32 v38, v56
	v_mov_b32_e32 v39, v56
	v_mov_b32_e32 v32, v56
	v_mov_b32_e32 v33, v56
	v_mov_b32_e32 v34, v56
	v_mov_b32_e32 v35, v56
	v_mov_b32_e32 v28, v56
	v_mov_b32_e32 v29, v56
	v_mov_b32_e32 v30, v56
	v_mov_b32_e32 v31, v56
	v_mov_b32_e32 v24, v56
	v_mov_b32_e32 v25, v56
	v_mov_b32_e32 v26, v56
	v_mov_b32_e32 v27, v56
	v_mov_b32_e32 v20, v56
	v_mov_b32_e32 v21, v56
	v_mov_b32_e32 v22, v56
	v_mov_b32_e32 v23, v56
	v_mov_b32_e32 v16, v56
	v_mov_b32_e32 v17, v56
	v_mov_b32_e32 v18, v56
	v_mov_b32_e32 v19, v56
	v_mov_b32_e32 v12, v56
	v_mov_b32_e32 v13, v56
	v_mov_b32_e32 v14, v56
	v_mov_b32_e32 v15, v56
	v_mov_b32_e32 v8, v56
	v_mov_b32_e32 v9, v56
	v_mov_b32_e32 v10, v56
	v_mov_b32_e32 v11, v56
	v_mov_b32_e32 v4, v56
	v_mov_b32_e32 v5, v56
	v_mov_b32_e32 v6, v56
	v_mov_b32_e32 v7, v56
	v_mov_b32_e32 v0, v56
	v_mov_b32_e32 v1, v56
	v_mov_b32_e32 v2, v56
	v_mov_b32_e32 v3, v56
	v_mov_b32_e32 v104, v56
	v_mov_b32_e32 v105, v56
